# speedup vs baseline: 1.1447x; 1.0048x over previous
; DEV f32x16 mfma(bf16x8 a, bf16x8 b, f32x16 c) { return __builtin_amdgcn_mfma_f32_32x32x16_bf16(a, b, c, 0, 0, 0); }
;     ...
;   for (int kt = 0; kt < nk; ++kt) {
;     if (kt + 1 < nk) { if (MI == 4) asm volatile("s_waitcnt vmcnt(6)" ::: "memory"); else asm volatile("s_waitcnt vmcnt(4)" ::: "memory"); } else asm volatile("s_waitcnt vmcnt(0)" ::: "memory");
;     __builtin_amdgcn_s_barrier();
;     if (kt + 2 < nk) { int s2 = stg + 2; if (s2 >= 3) s2 -= 3; g2_issue<MI>(ag + (size_t)(kt + 2) * 32, bg + (size_t)(kt + 2) * 32, lda, ldb, voffa, voffb, lds + s2 * G2_STAGE, w); }
;     const unsigned so = (unsigned)(stg * G2_STAGE);
;     __builtin_amdgcn_s_setprio(1);
; #pragma unroll
;     for (int ks = 0; ks < 2; ++ks) {
;       const unsigned aa = (ks ? la1 : la0) + so, bb = (ks ? lb1 : lb0) + so;
;       bf16x8 fb0, fb1, fa0, fa1, fa2, fa3;
;       asm volatile("ds_read_b128 %0, %1" : "=v"(fb0) : "v"(bb));
;       asm volatile("ds_read_b128 %0, %1 offset:2048" : "=v"(fb1) : "v"(bb));
;       asm volatile("ds_read_b128 %0, %1" : "=v"(fa0) : "v"(aa));
;       asm volatile("ds_read_b128 %0, %1 offset:2048" : "=v"(fa1) : "v"(aa));
;       if constexpr (MI == 4) {
;         asm volatile("ds_read_b128 %0, %1 offset:4096" : "=v"(fa2) : "v"(aa));
;         asm volatile("ds_read_b128 %0, %1 offset:6144" : "=v"(fa3) : "v"(aa));
;         __builtin_amdgcn_sched_barrier(0);
;         asm volatile("s_waitcnt lgkmcnt(3)" : "+v"(fb0), "+v"(fb1), "+v"(fa0));
;         acc[0][0][0] = mfma(fa0, fb0, acc[0][0][0]); acc[0][0][1] = mfma(fa0, fb1, acc[0][0][1]); __builtin_amdgcn_sched_barrier(0);
;         asm volatile("s_waitcnt lgkmcnt(2)" : "+v"(fa1));
;         acc[0][1][0] = mfma(fa1, fb0, acc[0][1][0]); acc[0][1][1] = mfma(fa1, fb1, acc[0][1][1]); __builtin_amdgcn_sched_barrier(0);
;         asm volatile("s_waitcnt lgkmcnt(1)" : "+v"(fa2));
;         acc[MI / 2 - 1][0][0] = mfma(fa2, fb0, acc[MI / 2 - 1][0][0]); acc[MI / 2 - 1][0][1] = mfma(fa2, fb1, acc[MI / 2 - 1][0][1]); __builtin_amdgcn_sched_barrier(0);
;         asm volatile("s_waitcnt lgkmcnt(0)" : "+v"(fa3));
;         acc[MI / 2 - 1][1][0] = mfma(fa3, fb0, acc[MI / 2 - 1][1][0]); acc[MI / 2 - 1][1][1] = mfma(fa3, fb1, acc[MI / 2 - 1][1][1]); __builtin_amdgcn_sched_barrier(0);
.LBB0_79:
	s_cmp_gt_i32 s6, 0
	s_cselect_b32 s81, -1, 2
	s_add_i32 s81, s81, s6
	s_mulk_i32 s81, 0x6000
	s_add_u32 s82, s7, s18
	s_addc_u32 s83, s80, s19
	s_add_i32 s84, s59, s81
	s_mul_i32 s99, s6, 0x6000
	s_setprio 1
	v_add_u32_e32 v147, s99, v141
	v_add_u32_e32 v149, s99, v143
	v_add_u32_e32 v172, v147, v145
	v_add_u32_e32 v156, v149, v145
	v_add_u32_e32 v147, v147, v138
	v_add_u32_e32 v149, v149, v138
	s_cmp_eq_u32 s18, 0
	s_cbranch_scc1 .Lhy10_first_down
	s_add_i32 s98, s6, 1
	s_cmp_lg_u32 s6, 2
	s_cselect_b32 s98, s98, 0
	s_mul_i32 s98, s98, 0x6000
	s_add_i32 s99, s59, s98
	v_add_u32_e32 v179, s99, v254
	s_add_i32 s99, s58, s98
	v_add_u32_e32 v241, s99, v254
	s_add_i32 s99, s57, s98
	v_add_u32_e32 v255, s99, v254
	s_waitcnt vmcnt(0)
	s_barrier
	ds_read_b128 v[152:155], v156
	ds_read_b128 v[156:159], v156 offset:2048
	ds_read_b128 v[160:163], v172
	ds_read_b128 v[164:167], v172 offset:2048
	ds_read_b128 v[168:171], v172 offset:4096
	ds_read_b128 v[172:175], v172 offset:6144
	ds_read_b128 v[180:183], v149
	ds_read_b128 v[184:187], v149 offset:2048
	ds_read_b128 v[188:191], v147
	ds_read_b128 v[242:245], v147 offset:2048
	ds_read_b128 v[246:249], v147 offset:4096
	ds_read_b128 v[250:253], v147 offset:6144
	ds_write_b128 v179, v[214:217]
	ds_write_b128 v241, v[218:221]
	ds_write_b128 v255, v[222:225]
	s_cmpk_eq_i32 s18, 0x2b80
	s_cbranch_scc1 .Lhy10_noissueE_down
	s_mov_b32 m0, s84
	s_nop 0
	global_load_lds_dwordx4 v1, s[82:83]
	global_load_dwordx4 v[214:217], v1, s[82:83] offset:64
	s_nop 0
	s_waitcnt lgkmcnt(9)
	s_nop 0
	v_mfma_f32_32x32x16_bf16 v[114:129], v[160:163], v[152:155], v[114:129]
	v_mfma_f32_32x32x16_bf16 v[98:113], v[160:163], v[156:159], v[98:113]
	s_add_u32 s82, s78, s18
	s_addc_u32 s83, s79, s19
	s_add_i32 s84, s58, s81
	s_mov_b32 m0, s84
	s_nop 0
	global_load_lds_dwordx4 v1, s[82:83]
	global_load_dwordx4 v[218:221], v1, s[82:83] offset:64
	s_waitcnt lgkmcnt(8)
	s_nop 0
	v_mfma_f32_32x32x16_bf16 v[82:97], v[164:167], v[152:155], v[82:97]
	v_mfma_f32_32x32x16_bf16 v[66:81], v[164:167], v[156:159], v[66:81]
	s_add_u32 s82, s76, s18
	s_addc_u32 s83, s77, s19
	s_add_i32 s84, s57, s81
	s_mov_b32 m0, s84
	s_nop 0
	global_load_lds_dwordx4 v1, s[82:83]
	global_load_dwordx4 v[222:225], v1, s[82:83] offset:64
	s_waitcnt lgkmcnt(7)
	s_nop 0
	v_mfma_f32_32x32x16_bf16 v[50:65], v[168:171], v[152:155], v[50:65]
	v_mfma_f32_32x32x16_bf16 v[34:49], v[168:171], v[156:159], v[34:49]
	s_waitcnt lgkmcnt(6)
	s_nop 0
	v_mfma_f32_32x32x16_bf16 v[18:33], v[172:175], v[152:155], v[18:33]
	v_mfma_f32_32x32x16_bf16 v[2:17], v[172:175], v[156:159], v[2:17]
	s_branch .Lhy10_afterE_down

; DEV f32x16 mfma(bf16x8 a, bf16x8 b, f32x16 c) { return __builtin_amdgcn_mfma_f32_32x32x16_bf16(a, b, c, 0, 0, 0); }
;     ...
;     if (kt + 2 < nk) { int s2 = stg + 2; if (s2 >= 3) s2 -= 3; g2_issue<MI>(ag + (size_t)(kt + 2) * 32, bg + (size_t)(kt + 2) * 32, lda, ldb, voffa, voffb, lds + s2 * G2_STAGE, w); }
;     const unsigned so = (unsigned)(stg * G2_STAGE);
;     __builtin_amdgcn_s_setprio(1);
; #pragma unroll
;     for (int ks = 0; ks < 2; ++ks) {
;       const unsigned aa = (ks ? la1 : la0) + so, bb = (ks ? lb1 : lb0) + so;
;       bf16x8 fb0, fb1, fa0, fa1, fa2, fa3;
;       asm volatile("ds_read_b128 %0, %1" : "=v"(fb0) : "v"(bb));
;       asm volatile("ds_read_b128 %0, %1 offset:2048" : "=v"(fb1) : "v"(bb));
;       asm volatile("ds_read_b128 %0, %1" : "=v"(fa0) : "v"(aa));
;       asm volatile("ds_read_b128 %0, %1 offset:2048" : "=v"(fa1) : "v"(aa));
;       if constexpr (MI == 4) {
;         asm volatile("ds_read_b128 %0, %1 offset:4096" : "=v"(fa2) : "v"(aa));
;         asm volatile("ds_read_b128 %0, %1 offset:6144" : "=v"(fa3) : "v"(aa));
;         __builtin_amdgcn_sched_barrier(0);
;         asm volatile("s_waitcnt lgkmcnt(3)" : "+v"(fb0), "+v"(fb1), "+v"(fa0));
;         acc[0][0][0] = mfma(fa0, fb0, acc[0][0][0]); acc[0][0][1] = mfma(fa0, fb1, acc[0][0][1]); __builtin_amdgcn_sched_barrier(0);
;         asm volatile("s_waitcnt lgkmcnt(2)" : "+v"(fa1));
;         acc[0][1][0] = mfma(fa1, fb0, acc[0][1][0]); acc[0][1][1] = mfma(fa1, fb1, acc[0][1][1]); __builtin_amdgcn_sched_barrier(0);
;         asm volatile("s_waitcnt lgkmcnt(1)" : "+v"(fa2));
;         acc[MI / 2 - 1][0][0] = mfma(fa2, fb0, acc[MI / 2 - 1][0][0]); acc[MI / 2 - 1][0][1] = mfma(fa2, fb1, acc[MI / 2 - 1][0][1]); __builtin_amdgcn_sched_barrier(0);
;         asm volatile("s_waitcnt lgkmcnt(0)" : "+v"(fa3));
;         acc[MI / 2 - 1][1][0] = mfma(fa3, fb0, acc[MI / 2 - 1][1][0]); acc[MI / 2 - 1][1][1] = mfma(fa3, fb1, acc[MI / 2 - 1][1][1]); __builtin_amdgcn_sched_barrier(0);
.Lhy10_first_down:
	s_waitcnt vmcnt(6)
	s_barrier
	ds_read_b128 v[152:155], v156
	ds_read_b128 v[156:159], v156 offset:2048
	ds_read_b128 v[160:163], v172
	ds_read_b128 v[164:167], v172 offset:2048
	ds_read_b128 v[168:171], v172 offset:4096
	ds_read_b128 v[172:175], v172 offset:6144
	ds_read_b128 v[180:183], v149
	ds_read_b128 v[184:187], v149 offset:2048
	ds_read_b128 v[188:191], v147
	ds_read_b128 v[242:245], v147 offset:2048
	ds_read_b128 v[246:249], v147 offset:4096
	ds_read_b128 v[250:253], v147 offset:6144
	s_cmpk_eq_i32 s18, 0x2b80
	s_cbranch_scc1 .Lhy10_noissueF_down
	s_mov_b32 m0, s84
	s_nop 0
	global_load_lds_dwordx4 v1, s[82:83]
	global_load_dwordx4 v[214:217], v1, s[82:83] offset:64
	s_nop 0
	s_waitcnt lgkmcnt(9)
	s_nop 0
	v_mfma_f32_32x32x16_bf16 v[114:129], v[160:163], v[152:155], v[114:129]
	v_mfma_f32_32x32x16_bf16 v[98:113], v[160:163], v[156:159], v[98:113]
	s_add_u32 s82, s78, s18
	s_addc_u32 s83, s79, s19
	s_add_i32 s84, s58, s81
	s_mov_b32 m0, s84
	s_nop 0
	global_load_lds_dwordx4 v1, s[82:83]
	global_load_dwordx4 v[218:221], v1, s[82:83] offset:64
	s_waitcnt lgkmcnt(8)
	s_nop 0
	v_mfma_f32_32x32x16_bf16 v[82:97], v[164:167], v[152:155], v[82:97]
	v_mfma_f32_32x32x16_bf16 v[66:81], v[164:167], v[156:159], v[66:81]
	s_add_u32 s82, s76, s18
	s_addc_u32 s83, s77, s19
	s_add_i32 s84, s57, s81
	s_mov_b32 m0, s84
	s_nop 0
	global_load_lds_dwordx4 v1, s[82:83]
	global_load_dwordx4 v[222:225], v1, s[82:83] offset:64
	s_waitcnt lgkmcnt(7)
	s_nop 0
	v_mfma_f32_32x32x16_bf16 v[50:65], v[168:171], v[152:155], v[50:65]
	v_mfma_f32_32x32x16_bf16 v[34:49], v[168:171], v[156:159], v[34:49]
	s_waitcnt lgkmcnt(6)
	s_nop 0
	v_mfma_f32_32x32x16_bf16 v[18:33], v[172:175], v[152:155], v[18:33]
	v_mfma_f32_32x32x16_bf16 v[2:17], v[172:175], v[156:159], v[2:17]
	s_branch .Lhy10_afterF_down

;     ...
;     if (kt + 1 < nk) { if (MI == 4) asm volatile("s_waitcnt vmcnt(6)" ::: "memory"); else asm volatile("s_waitcnt vmcnt(4)" ::: "memory"); } else asm volatile("s_waitcnt vmcnt(0)" ::: "memory");
;     __builtin_amdgcn_s_barrier();
;     if (kt + 2 < nk) { int s2 = stg + 2; if (s2 >= 3) s2 -= 3; g2_issue<MI>(ag + (size_t)(kt + 2) * 32, bg + (size_t)(kt + 2) * 32, lda, ldb, voffa, voffb, lds + s2 * G2_STAGE, w); }
;     const unsigned so = (unsigned)(stg * G2_STAGE);
;     __builtin_amdgcn_s_setprio(1);
; #pragma unroll
;     for (int ks = 0; ks < 2; ++ks) {
;       const unsigned aa = (ks ? la1 : la0) + so, bb = (ks ? lb1 : lb0) + so;
;       bf16x8 fb0, fb1, fa0, fa1, fa2, fa3;
;       asm volatile("ds_read_b128 %0, %1" : "=v"(fb0) : "v"(bb));
;       asm volatile("ds_read_b128 %0, %1 offset:2048" : "=v"(fb1) : "v"(bb));
;       asm volatile("ds_read_b128 %0, %1" : "=v"(fa0) : "v"(aa));
;       asm volatile("ds_read_b128 %0, %1 offset:2048" : "=v"(fa1) : "v"(aa));
;       if constexpr (MI == 4) {
;         asm volatile("ds_read_b128 %0, %1 offset:4096" : "=v"(fa2) : "v"(aa));
;         asm volatile("ds_read_b128 %0, %1 offset:6144" : "=v"(fa3) : "v"(aa));
;         __builtin_amdgcn_sched_barrier(0);
;         asm volatile("s_waitcnt lgkmcnt(3)" : "+v"(fb0), "+v"(fb1), "+v"(fa0));
;         acc[0][0][0] = mfma(fa0, fb0, acc[0][0][0]); acc[0][0][1] = mfma(fa0, fb1, acc[0][0][1]); __builtin_amdgcn_sched_barrier(0);
;         asm volatile("s_waitcnt lgkmcnt(2)" : "+v"(fa1));
;         acc[0][1][0] = mfma(fa1, fb0, acc[0][1][0]); acc[0][1][1] = mfma(fa1, fb1, acc[0][1][1]); __builtin_amdgcn_sched_barrier(0);
;         asm volatile("s_waitcnt lgkmcnt(1)" : "+v"(fa2));
;         acc[MI / 2 - 1][0][0] = mfma(fa2, fb0, acc[MI / 2 - 1][0][0]); acc[MI / 2 - 1][0][1] = mfma(fa2, fb1, acc[MI / 2 - 1][0][1]); __builtin_amdgcn_sched_barrier(0);
;         asm volatile("s_waitcnt lgkmcnt(0)" : "+v"(fa3));
;         acc[MI / 2 - 1][1][0] = mfma(fa3, fb0, acc[MI / 2 - 1][1][0]); acc[MI / 2 - 1][1][1] = mfma(fa3, fb1, acc[MI / 2 - 1][1][1]); __builtin_amdgcn_sched_barrier(0);
;       } else {
;         __builtin_amdgcn_sched_barrier(0);
;         asm volatile("s_waitcnt lgkmcnt(1)" : "+v"(fb0), "+v"(fb1), "+v"(fa0));
;         acc[0][0][0] = mfma(fa0, fb0, acc[0][0][0]); acc[0][0][1] = mfma(fa0, fb1, acc[0][0][1]); __builtin_amdgcn_sched_barrier(0);
.Lhy10_odd_down:
	s_setprio 0
	s_add_i32 s98, s6, 1
	s_cmp_lg_u32 s6, 2
	s_cselect_b32 s6, s98, 0
	s_mul_i32 s99, s6, 0x6000
	s_setprio 1
	v_add_u32_e32 v147, s99, v141
	v_add_u32_e32 v149, s99, v143
	v_add_u32_e32 v172, v147, v145
	v_add_u32_e32 v156, v149, v145
	v_add_u32_e32 v147, v147, v138
	v_add_u32_e32 v149, v149, v138
	s_waitcnt vmcnt(6) lgkmcnt(0)
	s_barrier
	ds_read_b128 v[152:155], v156
	ds_read_b128 v[156:159], v156 offset:2048
	ds_read_b128 v[160:163], v172
	ds_read_b128 v[164:167], v172 offset:2048
	ds_read_b128 v[168:171], v172 offset:4096
	ds_read_b128 v[172:175], v172 offset:6144
	ds_read_b128 v[180:183], v149
	ds_read_b128 v[184:187], v149 offset:2048
	ds_read_b128 v[188:191], v147
	ds_read_b128 v[242:245], v147 offset:2048
	ds_read_b128 v[246:249], v147 offset:4096
	ds_read_b128 v[250:253], v147 offset:6144
	s_cmpk_eq_i32 s18, 0x2b80
	s_cbranch_scc1 .Lhy10_noissueO_down
	s_add_u32 s82, s74, s18
	s_addc_u32 s83, s75, s19
	s_add_i32 s84, s56, s81
	s_addk_i32 s81, 0x4000
	s_mov_b32 m0, s84
	s_nop 0
	global_load_lds_dwordx4 v1, s[82:83]
	global_load_dwordx4 v[226:229], v1, s[82:83] offset:64
	s_nop 0
	s_waitcnt lgkmcnt(9)
	s_nop 0
	v_mfma_f32_32x32x16_bf16 v[114:129], v[160:163], v[152:155], v[114:129]
	v_mfma_f32_32x32x16_bf16 v[98:113], v[160:163], v[156:159], v[98:113]
	s_add_u32 s82, s63, s18
	s_addc_u32 s83, s64, s19
	s_add_i32 s84, s81, s55
	s_mov_b32 m0, s84
	s_nop 0
	global_load_lds_dwordx4 v1, s[82:83]
	global_load_dwordx4 v[230:233], v1, s[82:83] offset:64
	s_waitcnt lgkmcnt(8)
	s_nop 0
	v_mfma_f32_32x32x16_bf16 v[82:97], v[164:167], v[152:155], v[82:97]
	v_mfma_f32_32x32x16_bf16 v[66:81], v[164:167], v[156:159], v[66:81]
	s_add_u32 s82, s60, s18
	s_addc_u32 s83, s61, s19
	s_add_i32 s81, s81, s54
	s_mov_b32 m0, s81
	s_nop 0
	global_load_lds_dwordx4 v1, s[82:83]
	global_load_dwordx4 v[234:237], v1, s[82:83] offset:64
	s_waitcnt lgkmcnt(7)
	s_nop 0
	v_mfma_f32_32x32x16_bf16 v[50:65], v[168:171], v[152:155], v[50:65]
	v_mfma_f32_32x32x16_bf16 v[34:49], v[168:171], v[156:159], v[34:49]
	s_waitcnt lgkmcnt(6)
	s_nop 0
	v_mfma_f32_32x32x16_bf16 v[18:33], v[172:175], v[152:155], v[18:33]
	v_mfma_f32_32x32x16_bf16 v[2:17], v[172:175], v[156:159], v[2:17]
	s_branch .Lhy10_afterO_down

; DEV f32x16 mfma(bf16x8 a, bf16x8 b, f32x16 c) { return __builtin_amdgcn_mfma_f32_32x32x16_bf16(a, b, c, 0, 0, 0); }
;     ...
;   for (int kt = 0; kt < nk; ++kt) {
;     if (kt + 1 < nk) { if (MI == 4) asm volatile("s_waitcnt vmcnt(6)" ::: "memory"); else asm volatile("s_waitcnt vmcnt(4)" ::: "memory"); } else asm volatile("s_waitcnt vmcnt(0)" ::: "memory");
;     __builtin_amdgcn_s_barrier();
;     if (kt + 2 < nk) { int s2 = stg + 2; if (s2 >= 3) s2 -= 3; g2_issue<MI>(ag + (size_t)(kt + 2) * 32, bg + (size_t)(kt + 2) * 32, lda, ldb, voffa, voffb, lds + s2 * G2_STAGE, w); }
;     const unsigned so = (unsigned)(stg * G2_STAGE);
;     __builtin_amdgcn_s_setprio(1);
; #pragma unroll
;     for (int ks = 0; ks < 2; ++ks) {
;       const unsigned aa = (ks ? la1 : la0) + so, bb = (ks ? lb1 : lb0) + so;
;       bf16x8 fb0, fb1, fa0, fa1, fa2, fa3;
;       asm volatile("ds_read_b128 %0, %1" : "=v"(fb0) : "v"(bb));
;       asm volatile("ds_read_b128 %0, %1 offset:2048" : "=v"(fb1) : "v"(bb));
;       asm volatile("ds_read_b128 %0, %1" : "=v"(fa0) : "v"(aa));
;       asm volatile("ds_read_b128 %0, %1 offset:2048" : "=v"(fa1) : "v"(aa));
;       if constexpr (MI == 4) {
;         asm volatile("ds_read_b128 %0, %1 offset:4096" : "=v"(fa2) : "v"(aa));
;         asm volatile("ds_read_b128 %0, %1 offset:6144" : "=v"(fa3) : "v"(aa));
;         __builtin_amdgcn_sched_barrier(0);
;         asm volatile("s_waitcnt lgkmcnt(3)" : "+v"(fb0), "+v"(fb1), "+v"(fa0));
;         acc[0][0][0] = mfma(fa0, fb0, acc[0][0][0]); acc[0][0][1] = mfma(fa0, fb1, acc[0][0][1]); __builtin_amdgcn_sched_barrier(0);
;         asm volatile("s_waitcnt lgkmcnt(2)" : "+v"(fa1));
;         acc[0][1][0] = mfma(fa1, fb0, acc[0][1][0]); acc[0][1][1] = mfma(fa1, fb1, acc[0][1][1]); __builtin_amdgcn_sched_barrier(0);
;         asm volatile("s_waitcnt lgkmcnt(1)" : "+v"(fa2));
;         acc[MI / 2 - 1][0][0] = mfma(fa2, fb0, acc[MI / 2 - 1][0][0]); acc[MI / 2 - 1][0][1] = mfma(fa2, fb1, acc[MI / 2 - 1][0][1]); __builtin_amdgcn_sched_barrier(0);
;         asm volatile("s_waitcnt lgkmcnt(0)" : "+v"(fa3));
;         acc[MI / 2 - 1][1][0] = mfma(fa3, fb0, acc[MI / 2 - 1][1][0]); acc[MI / 2 - 1][1][1] = mfma(fa3, fb1, acc[MI / 2 - 1][1][1]); __builtin_amdgcn_sched_barrier(0);
.LBB0_118:
	s_cmp_gt_i32 s80, 0
	s_cselect_b32 s81, -1, 2
	s_add_i32 s81, s81, s80
	s_mulk_i32 s81, 0x6000
	s_add_u32 s82, s6, s22
	s_addc_u32 s83, s7, s23
	s_add_i32 s84, s59, s81
	s_mul_i32 s99, s80, 0x6000
	s_setprio 1
	v_add_u32_e32 v149, s99, v138
	v_add_u32_e32 v176, s99, v141
	v_add_u32_e32 v172, v149, v145
	v_add_u32_e32 v156, v176, v145
	v_add_u32_e32 v238, v176, v143
	v_add_u32_e32 v149, v149, v143
	s_cmp_eq_u32 s22, 0
	s_cbranch_scc1 .Lhy10_first_up
	s_add_i32 s98, s80, 1
	s_cmp_lg_u32 s80, 2
	s_cselect_b32 s98, s98, 0
	s_mul_i32 s98, s98, 0x6000
	s_add_i32 s99, s59, s98
	v_add_u32_e32 v179, s99, v254
	s_add_i32 s99, s58, s98
	v_add_u32_e32 v241, s99, v254
	s_add_i32 s99, s57, s98
	v_add_u32_e32 v255, s99, v254
	s_waitcnt vmcnt(0)
	s_barrier
	ds_read_b128 v[152:155], v156
	ds_read_b128 v[156:159], v156 offset:2048
	ds_read_b128 v[160:163], v172
	ds_read_b128 v[164:167], v172 offset:2048
	ds_read_b128 v[168:171], v172 offset:4096
	ds_read_b128 v[172:175], v172 offset:6144
	ds_read_b128 v[180:183], v238
	ds_read_b128 v[184:187], v238 offset:2048
	ds_read_b128 v[188:191], v149
	ds_read_b128 v[242:245], v149 offset:2048
	ds_read_b128 v[246:249], v149 offset:4096
	ds_read_b128 v[250:253], v149 offset:6144
	ds_write_b128 v179, v[214:217]
	ds_write_b128 v241, v[218:221]
	ds_write_b128 v255, v[222:225]
	s_cmpk_eq_i32 s22, 0xf80
	s_cbranch_scc1 .Lhy10_noissueE_up
	s_mov_b32 m0, s84
	s_nop 0
	global_load_lds_dwordx4 v1, s[82:83]
	global_load_dwordx4 v[214:217], v1, s[82:83] offset:64
	s_nop 0
	s_waitcnt lgkmcnt(9)
	s_nop 0
	v_mfma_f32_32x32x16_bf16 v[114:129], v[160:163], v[152:155], v[114:129]
	v_mfma_f32_32x32x16_bf16 v[98:113], v[160:163], v[156:159], v[98:113]
	s_add_u32 s82, s78, s22
	s_addc_u32 s83, s79, s23
	s_add_i32 s84, s58, s81
	s_mov_b32 m0, s84
	s_nop 0
	global_load_lds_dwordx4 v1, s[82:83]
	global_load_dwordx4 v[218:221], v1, s[82:83] offset:64
	s_waitcnt lgkmcnt(8)
	s_nop 0
	v_mfma_f32_32x32x16_bf16 v[82:97], v[164:167], v[152:155], v[82:97]
	v_mfma_f32_32x32x16_bf16 v[66:81], v[164:167], v[156:159], v[66:81]
	s_add_u32 s82, s76, s22
	s_addc_u32 s83, s77, s23
	s_add_i32 s84, s57, s81
	s_mov_b32 m0, s84
	s_nop 0
	global_load_lds_dwordx4 v1, s[82:83]
	global_load_dwordx4 v[222:225], v1, s[82:83] offset:64
	s_waitcnt lgkmcnt(7)
	s_nop 0
	v_mfma_f32_32x32x16_bf16 v[50:65], v[168:171], v[152:155], v[50:65]
	v_mfma_f32_32x32x16_bf16 v[34:49], v[168:171], v[156:159], v[34:49]
	s_waitcnt lgkmcnt(6)
	s_nop 0
	v_mfma_f32_32x32x16_bf16 v[18:33], v[172:175], v[152:155], v[18:33]
	v_mfma_f32_32x32x16_bf16 v[2:17], v[172:175], v[156:159], v[2:17]
	s_branch .Lhy10_afterE_up

; DEV f32x16 mfma(bf16x8 a, bf16x8 b, f32x16 c) { return __builtin_amdgcn_mfma_f32_32x32x16_bf16(a, b, c, 0, 0, 0); }
;     ...
;     if (kt + 2 < nk) { int s2 = stg + 2; if (s2 >= 3) s2 -= 3; g2_issue<MI>(ag + (size_t)(kt + 2) * 32, bg + (size_t)(kt + 2) * 32, lda, ldb, voffa, voffb, lds + s2 * G2_STAGE, w); }
;     const unsigned so = (unsigned)(stg * G2_STAGE);
;     __builtin_amdgcn_s_setprio(1);
; #pragma unroll
;     for (int ks = 0; ks < 2; ++ks) {
;       const unsigned aa = (ks ? la1 : la0) + so, bb = (ks ? lb1 : lb0) + so;
;       bf16x8 fb0, fb1, fa0, fa1, fa2, fa3;
;       asm volatile("ds_read_b128 %0, %1" : "=v"(fb0) : "v"(bb));
;       asm volatile("ds_read_b128 %0, %1 offset:2048" : "=v"(fb1) : "v"(bb));
;       asm volatile("ds_read_b128 %0, %1" : "=v"(fa0) : "v"(aa));
;       asm volatile("ds_read_b128 %0, %1 offset:2048" : "=v"(fa1) : "v"(aa));
;       if constexpr (MI == 4) {
;         asm volatile("ds_read_b128 %0, %1 offset:4096" : "=v"(fa2) : "v"(aa));
;         asm volatile("ds_read_b128 %0, %1 offset:6144" : "=v"(fa3) : "v"(aa));
;         __builtin_amdgcn_sched_barrier(0);
;         asm volatile("s_waitcnt lgkmcnt(3)" : "+v"(fb0), "+v"(fb1), "+v"(fa0));
;         acc[0][0][0] = mfma(fa0, fb0, acc[0][0][0]); acc[0][0][1] = mfma(fa0, fb1, acc[0][0][1]); __builtin_amdgcn_sched_barrier(0);
;         asm volatile("s_waitcnt lgkmcnt(2)" : "+v"(fa1));
;         acc[0][1][0] = mfma(fa1, fb0, acc[0][1][0]); acc[0][1][1] = mfma(fa1, fb1, acc[0][1][1]); __builtin_amdgcn_sched_barrier(0);
;         asm volatile("s_waitcnt lgkmcnt(1)" : "+v"(fa2));
;         acc[MI / 2 - 1][0][0] = mfma(fa2, fb0, acc[MI / 2 - 1][0][0]); acc[MI / 2 - 1][0][1] = mfma(fa2, fb1, acc[MI / 2 - 1][0][1]); __builtin_amdgcn_sched_barrier(0);
;         asm volatile("s_waitcnt lgkmcnt(0)" : "+v"(fa3));
;         acc[MI / 2 - 1][1][0] = mfma(fa3, fb0, acc[MI / 2 - 1][1][0]); acc[MI / 2 - 1][1][1] = mfma(fa3, fb1, acc[MI / 2 - 1][1][1]); __builtin_amdgcn_sched_barrier(0);
.Lhy10_first_up:
	s_waitcnt vmcnt(6)
	s_barrier
	ds_read_b128 v[152:155], v156
	ds_read_b128 v[156:159], v156 offset:2048
	ds_read_b128 v[160:163], v172
	ds_read_b128 v[164:167], v172 offset:2048
	ds_read_b128 v[168:171], v172 offset:4096
	ds_read_b128 v[172:175], v172 offset:6144
	ds_read_b128 v[180:183], v238
	ds_read_b128 v[184:187], v238 offset:2048
	ds_read_b128 v[188:191], v149
	ds_read_b128 v[242:245], v149 offset:2048
	ds_read_b128 v[246:249], v149 offset:4096
	ds_read_b128 v[250:253], v149 offset:6144
	s_cmpk_eq_i32 s22, 0xf80
	s_cbranch_scc1 .Lhy10_noissueF_up
	s_mov_b32 m0, s84
	s_nop 0
	global_load_lds_dwordx4 v1, s[82:83]
	global_load_dwordx4 v[214:217], v1, s[82:83] offset:64
	s_nop 0
	s_waitcnt lgkmcnt(9)
	s_nop 0
	v_mfma_f32_32x32x16_bf16 v[114:129], v[160:163], v[152:155], v[114:129]
	v_mfma_f32_32x32x16_bf16 v[98:113], v[160:163], v[156:159], v[98:113]
	s_add_u32 s82, s78, s22
	s_addc_u32 s83, s79, s23
	s_add_i32 s84, s58, s81
	s_mov_b32 m0, s84
	s_nop 0
	global_load_lds_dwordx4 v1, s[82:83]
	global_load_dwordx4 v[218:221], v1, s[82:83] offset:64
	s_waitcnt lgkmcnt(8)
	s_nop 0
	v_mfma_f32_32x32x16_bf16 v[82:97], v[164:167], v[152:155], v[82:97]
	v_mfma_f32_32x32x16_bf16 v[66:81], v[164:167], v[156:159], v[66:81]
	s_add_u32 s82, s76, s22
	s_addc_u32 s83, s77, s23
	s_add_i32 s84, s57, s81
	s_mov_b32 m0, s84
	s_nop 0
	global_load_lds_dwordx4 v1, s[82:83]
	global_load_dwordx4 v[222:225], v1, s[82:83] offset:64
	s_waitcnt lgkmcnt(7)
	s_nop 0
	v_mfma_f32_32x32x16_bf16 v[50:65], v[168:171], v[152:155], v[50:65]
	v_mfma_f32_32x32x16_bf16 v[34:49], v[168:171], v[156:159], v[34:49]
	s_waitcnt lgkmcnt(6)
	s_nop 0
	v_mfma_f32_32x32x16_bf16 v[18:33], v[172:175], v[152:155], v[18:33]
	v_mfma_f32_32x32x16_bf16 v[2:17], v[172:175], v[156:159], v[2:17]
	s_branch .Lhy10_afterF_up

;     ...
;     if (kt + 1 < nk) { if (MI == 4) asm volatile("s_waitcnt vmcnt(6)" ::: "memory"); else asm volatile("s_waitcnt vmcnt(4)" ::: "memory"); } else asm volatile("s_waitcnt vmcnt(0)" ::: "memory");
;     __builtin_amdgcn_s_barrier();
;     if (kt + 2 < nk) { int s2 = stg + 2; if (s2 >= 3) s2 -= 3; g2_issue<MI>(ag + (size_t)(kt + 2) * 32, bg + (size_t)(kt + 2) * 32, lda, ldb, voffa, voffb, lds + s2 * G2_STAGE, w); }
;     const unsigned so = (unsigned)(stg * G2_STAGE);
;     __builtin_amdgcn_s_setprio(1);
; #pragma unroll
;     for (int ks = 0; ks < 2; ++ks) {
;       const unsigned aa = (ks ? la1 : la0) + so, bb = (ks ? lb1 : lb0) + so;
;       bf16x8 fb0, fb1, fa0, fa1, fa2, fa3;
;       asm volatile("ds_read_b128 %0, %1" : "=v"(fb0) : "v"(bb));
;       asm volatile("ds_read_b128 %0, %1 offset:2048" : "=v"(fb1) : "v"(bb));
;       asm volatile("ds_read_b128 %0, %1" : "=v"(fa0) : "v"(aa));
;       asm volatile("ds_read_b128 %0, %1 offset:2048" : "=v"(fa1) : "v"(aa));
;       if constexpr (MI == 4) {
;         asm volatile("ds_read_b128 %0, %1 offset:4096" : "=v"(fa2) : "v"(aa));
;         asm volatile("ds_read_b128 %0, %1 offset:6144" : "=v"(fa3) : "v"(aa));
;         __builtin_amdgcn_sched_barrier(0);
;         asm volatile("s_waitcnt lgkmcnt(3)" : "+v"(fb0), "+v"(fb1), "+v"(fa0));
;         acc[0][0][0] = mfma(fa0, fb0, acc[0][0][0]); acc[0][0][1] = mfma(fa0, fb1, acc[0][0][1]); __builtin_amdgcn_sched_barrier(0);
;         asm volatile("s_waitcnt lgkmcnt(2)" : "+v"(fa1));
;         acc[0][1][0] = mfma(fa1, fb0, acc[0][1][0]); acc[0][1][1] = mfma(fa1, fb1, acc[0][1][1]); __builtin_amdgcn_sched_barrier(0);
;         asm volatile("s_waitcnt lgkmcnt(1)" : "+v"(fa2));
;         acc[MI / 2 - 1][0][0] = mfma(fa2, fb0, acc[MI / 2 - 1][0][0]); acc[MI / 2 - 1][0][1] = mfma(fa2, fb1, acc[MI / 2 - 1][0][1]); __builtin_amdgcn_sched_barrier(0);
;         asm volatile("s_waitcnt lgkmcnt(0)" : "+v"(fa3));
;         acc[MI / 2 - 1][1][0] = mfma(fa3, fb0, acc[MI / 2 - 1][1][0]); acc[MI / 2 - 1][1][1] = mfma(fa3, fb1, acc[MI / 2 - 1][1][1]); __builtin_amdgcn_sched_barrier(0);
;       } else {
;         __builtin_amdgcn_sched_barrier(0);
;         asm volatile("s_waitcnt lgkmcnt(1)" : "+v"(fb0), "+v"(fb1), "+v"(fa0));
;         acc[0][0][0] = mfma(fa0, fb0, acc[0][0][0]); acc[0][0][1] = mfma(fa0, fb1, acc[0][0][1]); __builtin_amdgcn_sched_barrier(0);
.Lhy10_odd_up:
	s_setprio 0
	s_add_i32 s98, s80, 1
	s_cmp_lg_u32 s80, 2
	s_cselect_b32 s80, s98, 0
	s_mul_i32 s99, s80, 0x6000
	s_setprio 1
	v_add_u32_e32 v149, s99, v138
	v_add_u32_e32 v176, s99, v141
	v_add_u32_e32 v172, v149, v145
	v_add_u32_e32 v156, v176, v145
	v_add_u32_e32 v238, v176, v143
	v_add_u32_e32 v149, v149, v143
	s_waitcnt vmcnt(6) lgkmcnt(0)
	s_barrier
	ds_read_b128 v[152:155], v156
	ds_read_b128 v[156:159], v156 offset:2048
	ds_read_b128 v[160:163], v172
	ds_read_b128 v[164:167], v172 offset:2048
	ds_read_b128 v[168:171], v172 offset:4096
	ds_read_b128 v[172:175], v172 offset:6144
	ds_read_b128 v[180:183], v238
	ds_read_b128 v[184:187], v238 offset:2048
	ds_read_b128 v[188:191], v149
	ds_read_b128 v[242:245], v149 offset:2048
	ds_read_b128 v[246:249], v149 offset:4096
	ds_read_b128 v[250:253], v149 offset:6144
	s_cmpk_eq_i32 s22, 0xf80
	s_cbranch_scc1 .Lhy10_noissueO_up
	s_add_u32 s82, s74, s22
	s_addc_u32 s83, s75, s23
	s_add_i32 s84, s56, s81
	s_addk_i32 s81, 0x4000
	s_mov_b32 m0, s84
	s_nop 0
	global_load_lds_dwordx4 v1, s[82:83]
	global_load_dwordx4 v[226:229], v1, s[82:83] offset:64
	s_nop 0
	s_waitcnt lgkmcnt(9)
	s_nop 0
	v_mfma_f32_32x32x16_bf16 v[114:129], v[160:163], v[152:155], v[114:129]
	v_mfma_f32_32x32x16_bf16 v[98:113], v[160:163], v[156:159], v[98:113]
	s_add_u32 s82, s63, s22
	s_addc_u32 s83, s64, s23
	s_add_i32 s84, s81, s55
	s_mov_b32 m0, s84
	s_nop 0
	global_load_lds_dwordx4 v1, s[82:83]
	global_load_dwordx4 v[230:233], v1, s[82:83] offset:64
	s_waitcnt lgkmcnt(8)
	s_nop 0
	v_mfma_f32_32x32x16_bf16 v[82:97], v[164:167], v[152:155], v[82:97]
	v_mfma_f32_32x32x16_bf16 v[66:81], v[164:167], v[156:159], v[66:81]
	s_add_u32 s82, s60, s22
	s_addc_u32 s83, s61, s23
	s_add_i32 s81, s81, s54
	s_mov_b32 m0, s81
	s_nop 0
	global_load_lds_dwordx4 v1, s[82:83]
	global_load_dwordx4 v[234:237], v1, s[82:83] offset:64
	s_waitcnt lgkmcnt(7)
	s_nop 0
	v_mfma_f32_32x32x16_bf16 v[50:65], v[168:171], v[152:155], v[50:65]
	v_mfma_f32_32x32x16_bf16 v[34:49], v[168:171], v[156:159], v[34:49]
	s_waitcnt lgkmcnt(6)
	s_nop 0
	v_mfma_f32_32x32x16_bf16 v[18:33], v[172:175], v[152:155], v[18:33]
	v_mfma_f32_32x32x16_bf16 v[2:17], v[172:175], v[156:159], v[2:17]
	s_branch .Lhy10_afterO_up

; DEV f32x16 mfma(bf16x8 a, bf16x8 b, f32x16 c) { return __builtin_amdgcn_mfma_f32_32x32x16_bf16(a, b, c, 0, 0, 0); }
;     ...
;   for (int kt = 0; kt < nk; ++kt) {
;     if (kt + 1 < nk) { if (MI == 4) asm volatile("s_waitcnt vmcnt(6)" ::: "memory"); else asm volatile("s_waitcnt vmcnt(4)" ::: "memory"); } else asm volatile("s_waitcnt vmcnt(0)" ::: "memory");
;     __builtin_amdgcn_s_barrier();
;     if (kt + 2 < nk) { int s2 = stg + 2; if (s2 >= 3) s2 -= 3; g2_issue<MI>(ag + (size_t)(kt + 2) * 32, bg + (size_t)(kt + 2) * 32, lda, ldb, voffa, voffb, lds + s2 * G2_STAGE, w); }
;     const unsigned so = (unsigned)(stg * G2_STAGE);
;     __builtin_amdgcn_s_setprio(1);
; #pragma unroll
;     for (int ks = 0; ks < 2; ++ks) {
;       const unsigned aa = (ks ? la1 : la0) + so, bb = (ks ? lb1 : lb0) + so;
;       bf16x8 fb0, fb1, fa0, fa1, fa2, fa3;
;       asm volatile("ds_read_b128 %0, %1" : "=v"(fb0) : "v"(bb));
;       asm volatile("ds_read_b128 %0, %1 offset:2048" : "=v"(fb1) : "v"(bb));
;       asm volatile("ds_read_b128 %0, %1" : "=v"(fa0) : "v"(aa));
;       asm volatile("ds_read_b128 %0, %1 offset:2048" : "=v"(fa1) : "v"(aa));
;       if constexpr (MI == 4) {
;         asm volatile("ds_read_b128 %0, %1 offset:4096" : "=v"(fa2) : "v"(aa));
;         asm volatile("ds_read_b128 %0, %1 offset:6144" : "=v"(fa3) : "v"(aa));
;         __builtin_amdgcn_sched_barrier(0);
;         asm volatile("s_waitcnt lgkmcnt(3)" : "+v"(fb0), "+v"(fb1), "+v"(fa0));
;         acc[0][0][0] = mfma(fa0, fb0, acc[0][0][0]); acc[0][0][1] = mfma(fa0, fb1, acc[0][0][1]); __builtin_amdgcn_sched_barrier(0);
;         asm volatile("s_waitcnt lgkmcnt(2)" : "+v"(fa1));
;         acc[0][1][0] = mfma(fa1, fb0, acc[0][1][0]); acc[0][1][1] = mfma(fa1, fb1, acc[0][1][1]); __builtin_amdgcn_sched_barrier(0);
;         asm volatile("s_waitcnt lgkmcnt(1)" : "+v"(fa2));
;         acc[MI / 2 - 1][0][0] = mfma(fa2, fb0, acc[MI / 2 - 1][0][0]); acc[MI / 2 - 1][0][1] = mfma(fa2, fb1, acc[MI / 2 - 1][0][1]); __builtin_amdgcn_sched_barrier(0);
;         asm volatile("s_waitcnt lgkmcnt(0)" : "+v"(fa3));
;         acc[MI / 2 - 1][1][0] = mfma(fa3, fb0, acc[MI / 2 - 1][1][0]); acc[MI / 2 - 1][1][1] = mfma(fa3, fb1, acc[MI / 2 - 1][1][1]); __builtin_amdgcn_sched_barrier(0);
.LBB0_537:
	s_cmp_gt_i32 s79, 0
	s_cselect_b32 s80, -1, 2
	s_add_i32 s80, s80, s79
	s_mul_i32 s82, s80, 0x6000
	s_add_u32 s80, s76, s18
	s_addc_u32 s81, s77, s19
	s_add_i32 s83, s1, s82
	s_mul_i32 s99, s79, 0x6000
	s_setprio 1
	v_add_u32_e32 v153, s99, v138
	v_add_u32_e32 v178, s99, v141
	v_add_u32_e32 v174, v153, v147
	v_add_u32_e32 v158, v178, v147
	v_add_u32_e32 v238, v178, v145
	v_add_u32_e32 v153, v153, v145
	s_cmp_eq_u32 s18, 0
	s_cbranch_scc1 .Lhy10_first_out
	s_add_i32 s98, s79, 1
	s_cmp_lg_u32 s79, 2
	s_cselect_b32 s98, s98, 0
	s_mul_i32 s98, s98, 0x6000
	s_add_i32 s99, s1, s98
	v_add_u32_e32 v179, s99, v254
	s_add_i32 s99, s26, s98
	v_add_u32_e32 v241, s99, v254
	s_add_i32 s99, s27, s98
	v_add_u32_e32 v255, s99, v254
	s_waitcnt vmcnt(0)
	s_barrier
	ds_read_b128 v[154:157], v158
	ds_read_b128 v[158:161], v158 offset:2048
	ds_read_b128 v[162:165], v174
	ds_read_b128 v[166:169], v174 offset:2048
	ds_read_b128 v[170:173], v174 offset:4096
	ds_read_b128 v[174:177], v174 offset:6144
	ds_read_b128 v[180:183], v238
	ds_read_b128 v[184:187], v238 offset:2048
	ds_read_b128 v[188:191], v153
	ds_read_b128 v[242:245], v153 offset:2048
	ds_read_b128 v[246:249], v153 offset:4096
	ds_read_b128 v[250:253], v153 offset:6144
	ds_write_b128 v179, v[214:217]
	ds_write_b128 v241, v[218:221]
	ds_write_b128 v255, v[222:225]
	s_cmpk_eq_i32 s18, 0xf80
	s_cbranch_scc1 .Lhy10_noissueE_out
	s_mov_b32 m0, s83
	s_nop 0
	global_load_lds_dwordx4 v1, s[80:81]
	global_load_dwordx4 v[214:217], v1, s[80:81] offset:64
	s_nop 0
	s_waitcnt lgkmcnt(9)
	s_nop 0
	v_mfma_f32_32x32x16_bf16 v[114:129], v[162:165], v[154:157], v[114:129]
	v_mfma_f32_32x32x16_bf16 v[98:113], v[162:165], v[158:161], v[98:113]
	s_add_u32 s80, s74, s18
	s_addc_u32 s81, s75, s19
	s_add_i32 s83, s26, s82
	s_mov_b32 m0, s83
	s_nop 0
	global_load_lds_dwordx4 v1, s[80:81]
	global_load_dwordx4 v[218:221], v1, s[80:81] offset:64
	s_waitcnt lgkmcnt(8)
	s_nop 0
	v_mfma_f32_32x32x16_bf16 v[82:97], v[166:169], v[154:157], v[82:97]
	v_mfma_f32_32x32x16_bf16 v[66:81], v[166:169], v[158:161], v[66:81]
	s_add_u32 s80, s59, s18
	s_addc_u32 s81, s63, s19
	s_add_i32 s83, s27, s82
	s_mov_b32 m0, s83
	s_nop 0
	global_load_lds_dwordx4 v1, s[80:81]
	global_load_dwordx4 v[222:225], v1, s[80:81] offset:64
	s_waitcnt lgkmcnt(7)
	s_nop 0
	v_mfma_f32_32x32x16_bf16 v[50:65], v[170:173], v[154:157], v[50:65]
	v_mfma_f32_32x32x16_bf16 v[34:49], v[170:173], v[158:161], v[34:49]
	s_waitcnt lgkmcnt(6)
	s_nop 0
	v_mfma_f32_32x32x16_bf16 v[18:33], v[174:177], v[154:157], v[18:33]
	v_mfma_f32_32x32x16_bf16 v[2:17], v[174:177], v[158:161], v[2:17]
	s_branch .Lhy10_afterE_out

; DEV f32x16 mfma(bf16x8 a, bf16x8 b, f32x16 c) { return __builtin_amdgcn_mfma_f32_32x32x16_bf16(a, b, c, 0, 0, 0); }
;     ...
;     if (kt + 2 < nk) { int s2 = stg + 2; if (s2 >= 3) s2 -= 3; g2_issue<MI>(ag + (size_t)(kt + 2) * 32, bg + (size_t)(kt + 2) * 32, lda, ldb, voffa, voffb, lds + s2 * G2_STAGE, w); }
;     const unsigned so = (unsigned)(stg * G2_STAGE);
;     __builtin_amdgcn_s_setprio(1);
; #pragma unroll
;     for (int ks = 0; ks < 2; ++ks) {
;       const unsigned aa = (ks ? la1 : la0) + so, bb = (ks ? lb1 : lb0) + so;
;       bf16x8 fb0, fb1, fa0, fa1, fa2, fa3;
;       asm volatile("ds_read_b128 %0, %1" : "=v"(fb0) : "v"(bb));
;       asm volatile("ds_read_b128 %0, %1 offset:2048" : "=v"(fb1) : "v"(bb));
;       asm volatile("ds_read_b128 %0, %1" : "=v"(fa0) : "v"(aa));
;       asm volatile("ds_read_b128 %0, %1 offset:2048" : "=v"(fa1) : "v"(aa));
;       if constexpr (MI == 4) {
;         asm volatile("ds_read_b128 %0, %1 offset:4096" : "=v"(fa2) : "v"(aa));
;         asm volatile("ds_read_b128 %0, %1 offset:6144" : "=v"(fa3) : "v"(aa));
;         __builtin_amdgcn_sched_barrier(0);
;         asm volatile("s_waitcnt lgkmcnt(3)" : "+v"(fb0), "+v"(fb1), "+v"(fa0));
;         acc[0][0][0] = mfma(fa0, fb0, acc[0][0][0]); acc[0][0][1] = mfma(fa0, fb1, acc[0][0][1]); __builtin_amdgcn_sched_barrier(0);
;         asm volatile("s_waitcnt lgkmcnt(2)" : "+v"(fa1));
;         acc[0][1][0] = mfma(fa1, fb0, acc[0][1][0]); acc[0][1][1] = mfma(fa1, fb1, acc[0][1][1]); __builtin_amdgcn_sched_barrier(0);
;         asm volatile("s_waitcnt lgkmcnt(1)" : "+v"(fa2));
;         acc[MI / 2 - 1][0][0] = mfma(fa2, fb0, acc[MI / 2 - 1][0][0]); acc[MI / 2 - 1][0][1] = mfma(fa2, fb1, acc[MI / 2 - 1][0][1]); __builtin_amdgcn_sched_barrier(0);
;         asm volatile("s_waitcnt lgkmcnt(0)" : "+v"(fa3));
;         acc[MI / 2 - 1][1][0] = mfma(fa3, fb0, acc[MI / 2 - 1][1][0]); acc[MI / 2 - 1][1][1] = mfma(fa3, fb1, acc[MI / 2 - 1][1][1]); __builtin_amdgcn_sched_barrier(0);
.Lhy10_first_out:
	s_waitcnt vmcnt(6)
	s_barrier
	ds_read_b128 v[154:157], v158
	ds_read_b128 v[158:161], v158 offset:2048
	ds_read_b128 v[162:165], v174
	ds_read_b128 v[166:169], v174 offset:2048
	ds_read_b128 v[170:173], v174 offset:4096
	ds_read_b128 v[174:177], v174 offset:6144
	ds_read_b128 v[180:183], v238
	ds_read_b128 v[184:187], v238 offset:2048
	ds_read_b128 v[188:191], v153
	ds_read_b128 v[242:245], v153 offset:2048
	ds_read_b128 v[246:249], v153 offset:4096
	ds_read_b128 v[250:253], v153 offset:6144
	s_cmpk_eq_i32 s18, 0xf80
	s_cbranch_scc1 .Lhy10_noissueF_out
	s_mov_b32 m0, s83
	s_nop 0
	global_load_lds_dwordx4 v1, s[80:81]
	global_load_dwordx4 v[214:217], v1, s[80:81] offset:64
	s_nop 0
	s_waitcnt lgkmcnt(9)
	s_nop 0
	v_mfma_f32_32x32x16_bf16 v[114:129], v[162:165], v[154:157], v[114:129]
	v_mfma_f32_32x32x16_bf16 v[98:113], v[162:165], v[158:161], v[98:113]
	s_add_u32 s80, s74, s18
	s_addc_u32 s81, s75, s19
	s_add_i32 s83, s26, s82
	s_mov_b32 m0, s83
	s_nop 0
	global_load_lds_dwordx4 v1, s[80:81]
	global_load_dwordx4 v[218:221], v1, s[80:81] offset:64
	s_waitcnt lgkmcnt(8)
	s_nop 0
	v_mfma_f32_32x32x16_bf16 v[82:97], v[166:169], v[154:157], v[82:97]
	v_mfma_f32_32x32x16_bf16 v[66:81], v[166:169], v[158:161], v[66:81]
	s_add_u32 s80, s59, s18
	s_addc_u32 s81, s63, s19
	s_add_i32 s83, s27, s82
	s_mov_b32 m0, s83
	s_nop 0
	global_load_lds_dwordx4 v1, s[80:81]
	global_load_dwordx4 v[222:225], v1, s[80:81] offset:64
	s_waitcnt lgkmcnt(7)
	s_nop 0
	v_mfma_f32_32x32x16_bf16 v[50:65], v[170:173], v[154:157], v[50:65]
	v_mfma_f32_32x32x16_bf16 v[34:49], v[170:173], v[158:161], v[34:49]
	s_waitcnt lgkmcnt(6)
	s_nop 0
	v_mfma_f32_32x32x16_bf16 v[18:33], v[174:177], v[154:157], v[18:33]
	v_mfma_f32_32x32x16_bf16 v[2:17], v[174:177], v[158:161], v[2:17]
	s_branch .Lhy10_afterF_out

;     ...
;     if (kt + 1 < nk) { if (MI == 4) asm volatile("s_waitcnt vmcnt(6)" ::: "memory"); else asm volatile("s_waitcnt vmcnt(4)" ::: "memory"); } else asm volatile("s_waitcnt vmcnt(0)" ::: "memory");
;     __builtin_amdgcn_s_barrier();
;     if (kt + 2 < nk) { int s2 = stg + 2; if (s2 >= 3) s2 -= 3; g2_issue<MI>(ag + (size_t)(kt + 2) * 32, bg + (size_t)(kt + 2) * 32, lda, ldb, voffa, voffb, lds + s2 * G2_STAGE, w); }
;     const unsigned so = (unsigned)(stg * G2_STAGE);
;     __builtin_amdgcn_s_setprio(1);
; #pragma unroll
;     for (int ks = 0; ks < 2; ++ks) {
;       const unsigned aa = (ks ? la1 : la0) + so, bb = (ks ? lb1 : lb0) + so;
;       bf16x8 fb0, fb1, fa0, fa1, fa2, fa3;
;       asm volatile("ds_read_b128 %0, %1" : "=v"(fb0) : "v"(bb));
;       asm volatile("ds_read_b128 %0, %1 offset:2048" : "=v"(fb1) : "v"(bb));
;       asm volatile("ds_read_b128 %0, %1" : "=v"(fa0) : "v"(aa));
;       asm volatile("ds_read_b128 %0, %1 offset:2048" : "=v"(fa1) : "v"(aa));
;       if constexpr (MI == 4) {
;         asm volatile("ds_read_b128 %0, %1 offset:4096" : "=v"(fa2) : "v"(aa));
;         asm volatile("ds_read_b128 %0, %1 offset:6144" : "=v"(fa3) : "v"(aa));
;         __builtin_amdgcn_sched_barrier(0);
;         asm volatile("s_waitcnt lgkmcnt(3)" : "+v"(fb0), "+v"(fb1), "+v"(fa0));
;         acc[0][0][0] = mfma(fa0, fb0, acc[0][0][0]); acc[0][0][1] = mfma(fa0, fb1, acc[0][0][1]); __builtin_amdgcn_sched_barrier(0);
;         asm volatile("s_waitcnt lgkmcnt(2)" : "+v"(fa1));
;         acc[0][1][0] = mfma(fa1, fb0, acc[0][1][0]); acc[0][1][1] = mfma(fa1, fb1, acc[0][1][1]); __builtin_amdgcn_sched_barrier(0);
;         asm volatile("s_waitcnt lgkmcnt(1)" : "+v"(fa2));
;         acc[MI / 2 - 1][0][0] = mfma(fa2, fb0, acc[MI / 2 - 1][0][0]); acc[MI / 2 - 1][0][1] = mfma(fa2, fb1, acc[MI / 2 - 1][0][1]); __builtin_amdgcn_sched_barrier(0);
;         asm volatile("s_waitcnt lgkmcnt(0)" : "+v"(fa3));
;         acc[MI / 2 - 1][1][0] = mfma(fa3, fb0, acc[MI / 2 - 1][1][0]); acc[MI / 2 - 1][1][1] = mfma(fa3, fb1, acc[MI / 2 - 1][1][1]); __builtin_amdgcn_sched_barrier(0);
;       } else {
;         __builtin_amdgcn_sched_barrier(0);
;         asm volatile("s_waitcnt lgkmcnt(1)" : "+v"(fb0), "+v"(fb1), "+v"(fa0));
;         acc[0][0][0] = mfma(fa0, fb0, acc[0][0][0]); acc[0][0][1] = mfma(fa0, fb1, acc[0][0][1]); __builtin_amdgcn_sched_barrier(0);
.Lhy10_odd_out:
	s_setprio 0
	s_add_i32 s98, s79, 1
	s_cmp_lg_u32 s79, 2
	s_cselect_b32 s79, s98, 0
	s_mul_i32 s99, s79, 0x6000
	s_setprio 1
	v_add_u32_e32 v153, s99, v138
	v_add_u32_e32 v178, s99, v141
	v_add_u32_e32 v174, v153, v147
	v_add_u32_e32 v158, v178, v147
	v_add_u32_e32 v238, v178, v145
	v_add_u32_e32 v153, v153, v145
	s_waitcnt vmcnt(6) lgkmcnt(0)
	s_barrier
	ds_read_b128 v[154:157], v158
	ds_read_b128 v[158:161], v158 offset:2048
	ds_read_b128 v[162:165], v174
	ds_read_b128 v[166:169], v174 offset:2048
	ds_read_b128 v[170:173], v174 offset:4096
	ds_read_b128 v[174:177], v174 offset:6144
	ds_read_b128 v[180:183], v238
	ds_read_b128 v[184:187], v238 offset:2048
	ds_read_b128 v[188:191], v153
	ds_read_b128 v[242:245], v153 offset:2048
	ds_read_b128 v[246:249], v153 offset:4096
	ds_read_b128 v[250:253], v153 offset:6144
	s_cmpk_eq_i32 s18, 0xf80
	s_cbranch_scc1 .Lhy10_noissueO_out
	s_add_u32 s80, s57, s18
	s_addc_u32 s81, s58, s19
	s_add_i32 s83, s28, s82
	s_addk_i32 s82, 0x4000
	s_mov_b32 m0, s83
	s_nop 0
	global_load_lds_dwordx4 v1, s[80:81]
	global_load_dwordx4 v[226:229], v1, s[80:81] offset:64
	s_nop 0
	s_waitcnt lgkmcnt(9)
	s_nop 0
	v_mfma_f32_32x32x16_bf16 v[114:129], v[162:165], v[154:157], v[114:129]
	v_mfma_f32_32x32x16_bf16 v[98:113], v[162:165], v[158:161], v[98:113]
	s_add_u32 s80, s20, s18
	s_addc_u32 s81, s21, s19
	s_add_i32 s83, s82, s30
	s_mov_b32 m0, s83
	s_nop 0
	global_load_lds_dwordx4 v1, s[80:81]
	global_load_dwordx4 v[230:233], v1, s[80:81] offset:64
	s_waitcnt lgkmcnt(8)
	s_nop 0
	v_mfma_f32_32x32x16_bf16 v[82:97], v[166:169], v[154:157], v[82:97]
	v_mfma_f32_32x32x16_bf16 v[66:81], v[166:169], v[158:161], v[66:81]
	s_add_u32 s80, s6, s18
	s_addc_u32 s81, s7, s19
	s_add_i32 s82, s82, s31
	s_mov_b32 m0, s82
	s_nop 0
	global_load_lds_dwordx4 v1, s[80:81]
	global_load_dwordx4 v[234:237], v1, s[80:81] offset:64
	s_waitcnt lgkmcnt(7)
	s_nop 0
	v_mfma_f32_32x32x16_bf16 v[50:65], v[170:173], v[154:157], v[50:65]
	v_mfma_f32_32x32x16_bf16 v[34:49], v[170:173], v[158:161], v[34:49]
	s_waitcnt lgkmcnt(6)
	s_nop 0
	v_mfma_f32_32x32x16_bf16 v[18:33], v[174:177], v[154:157], v[18:33]
	v_mfma_f32_32x32x16_bf16 v[2:17], v[174:177], v[158:161], v[2:17]
	s_branch .Lhy10_afterO_out
